# FFN up/gate GEMM phase: workgroups with one unit fewer start half a unit late (desynchronise epilogues chip-wide for smoother power)
# speedup vs baseline: 1.0051x; 1.0051x over previous
;     __device__ __forceinline__ bool next(int i, Unit& u) const {
;         const int L = i * G + c, nmain = nfull + (nwg - nfull) * nsplit; const bool ok = L < nmain + nex; const bool ex = L >= nmain;
;         const int e = ex ? L - nmain : 0;
;         const bool sp = !ex && L >= nfull; const int es = sp ? L - nfull : 0;
;         const int wgid = ex ? 0 : (sp ? nfull + es / nsplit : L);
;         int pm0, pn0; map(wgid, pm0, pn0);
;         u.pm = ex ? e / exN : pm0; u.pn = ex ? e % exN : pn0; u.gid = ex ? 1 : 0; u.ks = sp ? es % nsplit : -1; u.tail = sp ? es / nsplit : 0;
; __global__ void __launch_bounds__(512, 2) fwd_kernel(Args a) {
;     ...
;     if (IN(8)) {
;         Order S; S.init(MT, 2 * DFF, G, bid);
;         EpiP7 E{XCH, SS3, GATE, o_pf, o_sf, c_ffn, w_fconv, TAILB, HEADU, HEADG};
;         gemm_phase<EpiP7>(lds, H2B, WUG, H2B, WUG, DM, S, E);
.LBB0_1141:
	v_readlane_b32 s8, v243, 39
	v_readlane_b32 s16, v243, 47
	v_readlane_b32 s17, v243, 48
	v_readlane_b32 s18, v243, 49
	v_readlane_b32 s19, v243, 50
	v_readlane_b32 s20, v243, 51
	v_readlane_b32 s21, v243, 52
	v_readlane_b32 s22, v243, 53
	v_readlane_b32 s23, v243, 54
	s_mov_b64 s[16:17], s[20:21]
	s_cmp_lt_i32 s80, 9
	v_readlane_b32 s14, v243, 45
	s_mov_b64 s[18:19], s[22:23]
	s_cselect_b64 s[4:5], -1, 0
	v_readlane_b32 s15, v243, 46
	s_add_u32 s14, s18, 0x25000000
	s_addc_u32 s15, s19, 0
	s_add_u32 s46, s18, 0x3ce00000
	s_addc_u32 s47, s19, 0
	s_add_u32 s50, s18, 0x3d600000
	s_addc_u32 s51, s19, 0
	s_and_b64 s[6:7], s[4:5], s[0:1]
	s_andn2_b64 vcc, exec, s[6:7]
	v_readlane_b32 s9, v243, 40
	v_readlane_b32 s10, v243, 41
	v_readlane_b32 s11, v243, 42
	v_readlane_b32 s12, v243, 43
	v_readlane_b32 s13, v243, 44
	s_cbranch_vccnz .LBB0_1199
	s_cmp_lt_u32 s2, 0x60
	s_cbranch_scc1 .Ldesync_p8_done
	s_memrealtime s[98:99]
	s_waitcnt lgkmcnt(0)
	s_add_u32 s100, s98, 2900
.Ldesync_p8_spin:
	s_sleep 8
	s_memrealtime s[98:99]
	s_waitcnt lgkmcnt(0)
	s_sub_u32 s99, s98, s100
	s_cmp_lt_i32 s99, 0
	s_cbranch_scc1 .Ldesync_p8_spin
.Ldesync_p8_done:
	s_cmpk_gt_i32 s2, 0x175f
	v_readfirstlane_b32 s4, v177
	s_cbranch_scc1 .LBB0_1144
	s_ashr_i32 s0, s2, 31
	s_lshr_b32 s0, s0, 29
	s_add_i32 s0, s2, s0
	s_ashr_i32 s1, s0, 3
	s_and_b32 s0, s0, -8
	s_sub_i32 s0, s2, s0
	s_cmp_lt_i32 s0, 0
	s_movk_i32 s3, 0x2ed
	s_cselect_b32 s3, s3, 0x2ec
	s_mul_i32 s0, s0, s3
	s_add_i32 s0, s0, s1
	s_mul_hi_i32 s1, s0, 0x2e8ba2e9
	s_lshr_b32 s3, s1, 31
	s_ashr_i32 s1, s1, 5
	s_add_i32 s1, s1, s3
	s_mul_i32 s3, s1, 0xb0
	s_sub_i32 s3, s0, s3
	s_bfe_u32 s0, s3, 0x2001d
	s_add_i32 s5, s3, s0
	s_sext_i32_i16 s0, s5
	s_and_b32 s5, s5, 0xfffc
	s_sub_i32 s3, s3, s5
	s_lshl_b32 s1, s1, 2
	s_sext_i32_i16 s3, s3
	s_ashr_i32 s0, s0, 2
	s_add_i32 s70, s1, s3
	s_cmpk_gt_i32 s2, 0x175f
	s_cbranch_scc0 .LBB0_1145
	s_branch .LBB0_1199
